# sample attention: K quarter-tile LDS writes issued at the end of the step next to the V writes, so the step head is only wait + barrier
# baseline (speedup 1.0000x reference)
; __device__ __forceinline__ void sattn_unit(const Args& a, LAS unsigned char* lds, const LAS float* bt, int db, int h, int t, int tid, int wave, int lane) {
;     ...
;     for (int it = 0; it < nf; ++it) {
;         const int key0 = __builtin_amdgcn_readfirstlane((tile0 + it) * 32);
;         bf16x8 kf[4]; bf16x8 vf[2][2];
;         SA_CVT();
;         if (it + 1 < nf) SA_LOAD(key0 + 32);
.Lks_m0:
	v_readlane_b32 s34, v251, 10
	v_mbcnt_lo_u32_b32 v250, -1, 0
	v_mbcnt_hi_u32_b32 v250, -1, v250
	s_lshr_b32 s14, s34, 2
	s_lshl_b32 s14, s14, 14
	s_add_i32 s14, s14, 0x12800
	s_bfe_u32 s15, s34, 0x10001
	s_lshl_b32 s15, s15, 12
	s_add_i32 s15, s15, s14
	v_lshrrev_b32_e32 v74, 5, v250
	v_and_b32_e32 v75, 31, v250
	v_lshlrev_b32_e32 v73, 8, v74
	v_lshl_add_u32 v73, v75, 1, v73
	v_add_u32_e32 v73, s15, v73
	v_cvt_pk_bf16_f32 v72, v176, v176
	ds_write_b16 v73, v72 offset:0
	v_cvt_pk_bf16_f32 v72, v179, v179
	ds_write_b16 v73, v72 offset:64
	v_cvt_pk_bf16_f32 v72, v195, v195
	ds_write_b16 v73, v72 offset:128
	v_cvt_pk_bf16_f32 v72, v204, v204
	ds_write_b16 v73, v72 offset:192
	v_cvt_pk_bf16_f32 v72, v219, v219
	ds_write_b16 v73, v72 offset:512
	v_cvt_pk_bf16_f32 v72, v228, v228
	ds_write_b16 v73, v72 offset:576
	v_cvt_pk_bf16_f32 v72, v239, v239
	ds_write_b16 v73, v72 offset:640
	v_cvt_pk_bf16_f32 v72, v242, v242
	ds_write_b16 v73, v72 offset:704
	v_cvt_pk_bf16_f32 v72, v175, v175
	ds_write_b16 v73, v72 offset:1024
	v_cvt_pk_bf16_f32 v72, v178, v178
	ds_write_b16 v73, v72 offset:1088
	v_cvt_pk_bf16_f32 v72, v186, v186
	ds_write_b16 v73, v72 offset:1152
	v_cvt_pk_bf16_f32 v72, v202, v202
	ds_write_b16 v73, v72 offset:1216
	v_cvt_pk_bf16_f32 v72, v218, v218
	ds_write_b16 v73, v72 offset:1536
	v_cvt_pk_bf16_f32 v72, v226, v226
	ds_write_b16 v73, v72 offset:1600
	v_cvt_pk_bf16_f32 v72, v238, v238
	ds_write_b16 v73, v72 offset:1664
	v_cvt_pk_bf16_f32 v72, v241, v241
	ds_write_b16 v73, v72 offset:1728
	v_cvt_pk_bf16_f32 v72, v174, v174
	ds_write_b16 v73, v72 offset:2048
	v_cvt_pk_bf16_f32 v72, v177, v177
	ds_write_b16 v73, v72 offset:2112
	v_cvt_pk_bf16_f32 v72, v184, v184
	ds_write_b16 v73, v72 offset:2176
	v_cvt_pk_bf16_f32 v72, v200, v200
	ds_write_b16 v73, v72 offset:2240
	v_cvt_pk_bf16_f32 v72, v216, v216
	ds_write_b16 v73, v72 offset:2560
	v_cvt_pk_bf16_f32 v72, v224, v224
	ds_write_b16 v73, v72 offset:2624
	v_cvt_pk_bf16_f32 v72, v237, v237
	ds_write_b16 v73, v72 offset:2688
	v_cvt_pk_bf16_f32 v72, v240, v240
	ds_write_b16 v73, v72 offset:2752
	v_cvt_pk_bf16_f32 v72, v173, v173
	ds_write_b16 v73, v72 offset:3072
	v_cvt_pk_bf16_f32 v72, v180, v180
	ds_write_b16 v73, v72 offset:3136
	v_cvt_pk_bf16_f32 v72, v183, v183
	ds_write_b16 v73, v72 offset:3200
	v_cvt_pk_bf16_f32 v72, v207, v207
	ds_write_b16 v73, v72 offset:3264
	v_cvt_pk_bf16_f32 v72, v214, v214
	ds_write_b16 v73, v72 offset:3584
	v_cvt_pk_bf16_f32 v72, v231, v231
	ds_write_b16 v73, v72 offset:3648
	v_cvt_pk_bf16_f32 v72, v236, v236
	ds_write_b16 v73, v72 offset:3712
	v_cvt_pk_bf16_f32 v72, v243, v243
	ds_write_b16 v73, v72 offset:3776
	v_bfe_u32 v76, v250, 4, 1
	v_lshlrev_b32_e32 v76, 5, v76
	v_and_b32_e32 v77, 3, v250
	v_lshl_add_u32 v76, v77, 3, v76
	v_bfe_u32 v77, v250, 2, 2
	v_lshl_add_u32 v77, v74, 2, v77
	v_lshl_add_u32 v249, v77, 6, v76
	v_add_u32_e32 v249, s15, v249
	s_and_b32 s15, s34, 3
	s_lshl_b32 s48, s15, 9
	s_add_i32 s48, s48, s14
	v_lshrrev_b32_e32 v76, 3, v75
	v_lshlrev_b32_e32 v76, 11, v76
	v_lshl_add_u32 v76, v74, 6, v76
	v_and_b32_e32 v77, 7, v250
	v_lshl_add_u32 v248, v77, 3, v76
	v_add_u32_e32 v248, s48, v248
	s_lshl_b32 s15, s15, 15
	v_lshlrev_b32_e32 v76, 12, v74
	v_lshl_add_u32 v250, v75, 4, v76
	v_add_u32_e32 v250, s15, v250
	s_mov_b32 s34, 0x2000
	s_lshl_b32 s81, s81, 15
	s_movk_i32 s32, 0x2200
	ds_write_b128 v172, v[64:67] offset:40960
	ds_write_b128 v172, v[68:71] offset:42048
.LBB0_295:
	s_waitcnt lgkmcnt(0)
	s_barrier
	ds_read_b64_tr_b16 v[72:73], v249
	ds_read_b64_tr_b16 v[74:75], v249 offset:512
	ds_read_b64_tr_b16 v[76:77], v249 offset:1024
	ds_read_b64_tr_b16 v[78:79], v249 offset:1536
	ds_read_b64_tr_b16 v[80:81], v249 offset:2048
	ds_read_b64_tr_b16 v[82:83], v249 offset:2560
	ds_read_b64_tr_b16 v[84:85], v249 offset:3072
	ds_read_b64_tr_b16 v[86:87], v249 offset:3584
	ds_read_b128 v[108:111], v170 offset:40960
	ds_read_b128 v[104:107], v170 offset:40976
	ds_read_b128 v[100:103], v170 offset:41024
	ds_read_b128 v[96:99], v170 offset:41040
	ds_read_b128 v[44:47], v170 offset:41088
	ds_read_b128 v[40:43], v170 offset:41104
	ds_read_b128 v[36:39], v170 offset:41152
	ds_read_b128 v[32:35], v170 offset:41168
	v_add_u32_e32 v170, s32, v170
	v_add_u32_e32 v172, s32, v172
	s_sub_i32 s32, 0, s32
	v_add_u32_e32 v249, s34, v249
	v_add_u32_e32 v248, s34, v248
	s_sub_i32 s34, 0, s34
	s_add_i32 s0, s96, s35
	s_lshl_b32 vcc_lo, s0, 5
	s_add_i32 s35, s35, 1
	s_cmp_ge_u32 s35, s97
	s_cbranch_scc1 .LBB0_297
	s_add_i32 s0, s30, vcc_lo
	s_ashr_i32 s1, s0, 31
	s_lshl_b64 s[0:1], s[0:1], 12
	s_lshl_b32 s14, s5, 2
	s_or_b32 s0, s0, s14
	s_add_u32 s48, s93, s0
	s_addc_u32 s49, s89, s1
	s_add_u32 s48, s48, s81
	s_addc_u32 s49, s49, 0
	s_add_u32 s0, s42, s0
	s_addc_u32 s1, s43, s1
	v_lshl_add_u64 v[64:65], v[112:113], 2, s[48:49]
	v_lshl_add_u64 v[68:69], v[120:121], 2, s[48:49]
	global_load_dwordx4 v[64:67], v[64:65], off
	s_nop 0
	global_load_dwordx4 v[68:71], v[68:69], off
	s_nop 0
	global_load_dwordx4 v[196:199], v250, s[0:1]
	s_add_u32 s14, s0, 0x2000
	s_addc_u32 s15, s1, 0
	global_load_dwordx4 v[200:203], v250, s[14:15]
	s_add_u32 s48, s0, 0x4000
	s_addc_u32 s49, s1, 0
	global_load_dwordx4 v[204:207], v250, s[48:49]
	s_add_u32 s14, s0, 0x6000
	s_addc_u32 s15, s1, 0
	global_load_dwordx4 v[208:211], v250, s[14:15]

.LBB0_301:
	v_sub_f32_e32 v32, v32, v104
	v_exp_f32_e32 v32, v32
	v_sub_f32_e32 v33, v33, v104
	v_exp_f32_e32 v33, v33
	v_sub_f32_e32 v34, v34, v104
	v_exp_f32_e32 v34, v34
	v_sub_f32_e32 v35, v35, v104
	v_sub_f32_e32 v36, v36, v104
	v_sub_f32_e32 v37, v37, v104
	v_sub_f32_e32 v38, v38, v104
	v_sub_f32_e32 v39, v39, v104
	v_exp_f32_e32 v35, v35
	v_exp_f32_e32 v36, v36
	v_exp_f32_e32 v37, v37
	v_exp_f32_e32 v38, v38
	v_exp_f32_e32 v39, v39
	v_add_f32_e32 v105, 0, v32
	v_add_f32_e32 v105, v33, v105
	v_add_f32_e32 v105, v34, v105
	v_add_f32_e32 v105, v35, v105
	v_cvt_pk_bf16_f32 v32, v32, v33
	v_cvt_pk_bf16_f32 v33, v34, v35
	v_cvt_pk_bf16_f32 v34, v36, v37
	v_cvt_pk_bf16_f32 v35, v38, v39
	v_sub_f32_e32 v40, v40, v104
	v_sub_f32_e32 v41, v41, v104
	v_sub_f32_e32 v42, v42, v104
	v_sub_f32_e32 v43, v43, v104
	v_sub_f32_e32 v44, v44, v104
	v_sub_f32_e32 v45, v45, v104
	v_sub_f32_e32 v46, v46, v104
	v_sub_f32_e32 v47, v47, v104
	v_exp_f32_e32 v40, v40
	v_exp_f32_e32 v41, v41
	v_exp_f32_e32 v42, v42
	v_exp_f32_e32 v43, v43
	v_exp_f32_e32 v44, v44
	v_exp_f32_e32 v45, v45
	v_exp_f32_e32 v46, v46
	v_exp_f32_e32 v47, v47
	v_add_f32_e32 v105, v36, v105
	v_mfma_f32_32x32x16_bf16 v[0:15], v[32:35], v[72:75], v[0:15]
	v_add_f32_e32 v105, v37, v105
	v_add_f32_e32 v105, v38, v105
	v_add_f32_e32 v105, v39, v105
	v_cvt_pk_bf16_f32 v36, v40, v41
	v_cvt_pk_bf16_f32 v37, v42, v43
	v_cvt_pk_bf16_f32 v38, v44, v45
	v_cvt_pk_bf16_f32 v39, v46, v47
	v_mfma_f32_32x32x16_bf16 v[16:31], v[32:35], v[80:83], v[16:31]
	v_add_f32_e32 v105, v40, v105
	v_add_f32_e32 v105, v41, v105
	v_mfma_f32_32x32x16_bf16 v[0:15], v[36:39], v[76:79], v[0:15]
	v_add_f32_e32 v105, v42, v105
	v_add_f32_e32 v105, v43, v105
	v_add_f32_e32 v105, v44, v105
	v_add_f32_e32 v105, v45, v105
	v_add_f32_e32 v105, v46, v105
	v_add_f32_e32 v105, v47, v105
	v_add_f32_e32 v169, v105, v169
	v_mfma_f32_32x32x16_bf16 v[16:31], v[36:39], v[84:87], v[16:31]
	s_cmp_eq_u32 s97, s35
	s_cbranch_scc1 .LBB0_303
	s_waitcnt vmcnt(0)
	v_cvt_pk_bf16_f32 v88, v196, v197
	v_cvt_pk_bf16_f32 v89, v198, v199
	v_cvt_pk_bf16_f32 v90, v200, v201
	v_cvt_pk_bf16_f32 v91, v202, v203
	v_cvt_pk_bf16_f32 v92, v204, v205
	v_cvt_pk_bf16_f32 v93, v206, v207
	v_cvt_pk_bf16_f32 v94, v208, v209
	v_cvt_pk_bf16_f32 v95, v210, v211
	ds_write_b64 v248, v[88:89]
	ds_write_b64 v248, v[90:91] offset:128
	ds_write_b64 v248, v[92:93] offset:256
	ds_write_b64 v248, v[94:95] offset:384
	ds_write_b128 v172, v[64:67] offset:40960
	ds_write_b128 v172, v[68:71] offset:42048
	v_mov_b32_e32 v244, v104
	s_branch .LBB0_295
